# attention: next tile QK_A MFMAs hoisted into step-B exp block
# speedup vs baseline: 1.0076x; 1.0004x over previous
.LBB0_262:
	s_cmpk_lt_i32 s18, 0x200
	s_mov_b64 s[0:1], -1
	s_cbranch_scc0 .LBB0_285
	s_mov_b64 s[8:9], s[36:37]
	v_mov_b32_e32 v12, v224
	s_load_dwordx2 s[2:3], s[8:9], 0xa8
	s_and_b32 s6, s22, 0xffffe000
	s_bfe_u32 s7, s18, 0x70001
	v_ashrrev_i32_e32 v0, 6, v12
	s_movk_i32 s4, 0x2400
	s_waitcnt lgkmcnt(0)
	s_add_u32 s0, s2, 0x6000000
	s_addc_u32 s1, s3, 0
	v_mul_lo_u32 v4, v0, s4
	s_lshl_b32 s4, s18, 5
	v_and_b32_e32 v252, 31, v12
	v_mul_lo_u32 v0, v0, s61
	s_and_b32 s11, s4, 0xffffe000
	s_lshl_b32 s5, s7, 6
	s_and_b32 s10, s4, 32
	v_add_u32_e32 v246, s19, v0
	s_or_b32 s5, s5, s11
	v_or_b32_e32 v0, s10, v252
	s_waitcnt vmcnt(10)
	v_or_b32_e32 v162, s5, v0
	v_mov_b64_e32 v[0:1], s[0:1]
	s_movk_i32 s4, 0x1c00
	v_mad_i64_i32 v[0:1], s[4:5], v162, s4, v[0:1]
	s_sub_i32 s4, 8, s7
	s_cmp_lt_u32 s7, 8
	s_cselect_b32 s29, s4, 0
	s_add_i32 s4, s29, s7
	s_lshl_b32 s7, s4, 6
	v_and_b32_e32 v164, 0xffffffc0, v12
	s_add_i32 s4, s11, s7
	v_ashrrev_i32_e32 v165, 31, v164
	s_addk_i32 s4, 0xfe00
	v_bfe_u32 v13, v12, 5, 1
	v_lshlrev_b64 v[2:3], 1, v[164:165]
	s_mul_hi_i32 s5, s4, 0x1c00
	s_mulk_i32 s4, 0x1c00
	v_lshl_add_u64 v[0:1], v[0:1], 0, v[2:3]
	v_lshlrev_b32_e32 v112, 4, v13
	s_add_u32 s4, s0, s4
	v_lshl_add_u64 v[0:1], v[0:1], 0, v[112:113]
	v_add_u32_e32 v15, s24, v4
	s_addc_u32 s5, s1, s5
	v_mul_u32_u24_e32 v4, 0xe00, v252
	global_load_dwordx4 v[64:67], v[0:1], off
	global_load_dwordx4 v[68:71], v[0:1], off offset:32
	global_load_dwordx4 v[72:75], v[0:1], off offset:64
	global_load_dwordx4 v[76:79], v[0:1], off offset:96
	v_lshl_add_u64 v[0:1], s[4:5], 0, v[2:3]
	v_lshlrev_b32_e32 v4, 1, v4
	v_mov_b32_e32 v5, v113
	v_lshl_add_u64 v[6:7], v[0:1], 0, v[4:5]
	v_lshl_add_u64 v[6:7], v[6:7], 0, v[112:113]
	ds_read_b32 v166, v246 offset:1276
	v_bfe_u32 v216, v12, 3, 3
	v_and_b32_e32 v217, 7, v12
	v_lshlrev_b32_e32 v213, 1, v164
	v_mad_u32_u24 v213, v216, v238, v213
	v_lshl_add_u32 v213, v217, 4, v213
	v_add_u32_e32 v213, 0x400, v213
	v_mul_u32_u24_e32 v214, 0x48, v164
	v_add_u32_e32 v214, 0x15000, v214
	v_add_u32_e32 v214, s24, v214
	v_mul_u32_u24_e32 v215, 0x90, v252
	v_lshl_add_u32 v215, v13, 4, v215
	v_add_u32_e32 v215, v215, v214
	v_mul_u32_u24_e32 v218, 0x90, v216
	v_lshl_add_u32 v218, v217, 4, v218
	v_add_u32_e32 v214, v214, v218
	s_mov_b64 s[38:39], s[4:5]
	global_load_dwordx4 v[80:83], v213, s[38:39]
	s_add_u32 s38, s38, 0xe000
	s_addc_u32 s39, s39, 0
	global_load_dwordx4 v[84:87], v213, s[38:39]
	s_add_u32 s38, s38, 0xe000
	s_addc_u32 s39, s39, 0
	global_load_dwordx4 v[88:91], v213, s[38:39]
	s_add_u32 s38, s38, 0xe000
	s_addc_u32 s39, s39, 0
	global_load_dwordx4 v[92:95], v213, s[38:39]
	s_add_u32 s38, s38, 0xe000
	s_addc_u32 s39, s39, 0
	v_bfe_u32 v16, v12, 3, 3
	v_lshlrev_b32_e32 v6, 4, v12
	v_and_b32_e32 v6, 0x70, v6
	v_mov_b32_e32 v7, v113
	v_mul_u32_u24_e32 v34, 0xe00, v16
	v_lshl_add_u64 v[0:1], v[0:1], 0, v[6:7]
	v_lshlrev_b32_e32 v8, 1, v34
	v_mov_b32_e32 v9, v113
	v_lshl_add_u64 v[8:9], v[0:1], 0, v[8:9]
	s_mov_b32 s4, 0xe000
	v_add_co_u32_e32 v10, vcc, s4, v8
	s_mov_b32 s4, 0x1c000
	s_nop 0
	v_addc_co_u32_e32 v11, vcc, 0, v9, vcc
	global_load_dwordx4 v[96:99], v[8:9], off offset:2048
	global_load_dwordx4 v[100:103], v[10:11], off offset:2048
	v_add_co_u32_e32 v10, vcc, s4, v8
	s_mov_b32 s4, 0x2a000
	s_nop 0
	v_addc_co_u32_e32 v11, vcc, 0, v9, vcc
	v_add_co_u32_e32 v8, vcc, s4, v8
	s_movk_i32 s4, 0xe00
	s_nop 0
	v_addc_co_u32_e32 v9, vcc, 0, v9, vcc
	global_load_dwordx4 v[104:107], v[10:11], off offset:2048
	global_load_dwordx4 v[108:111], v[8:9], off offset:2048
	v_mov_b32_e32 v8, 0x1c000
	v_mad_u32_u24 v36, v16, s4, v8
	v_mov_b32_e32 v10, 0x23000
	v_lshlrev_b32_e32 v8, 1, v36
	v_mov_b32_e32 v9, v113
	v_mad_u32_u24 v38, v16, s4, v10
	v_lshl_add_u64 v[8:9], v[0:1], 0, v[8:9]
	v_lshlrev_b32_e32 v10, 1, v38
	v_mov_b32_e32 v11, v113
	v_lshl_add_u64 v[10:11], v[0:1], 0, v[10:11]
	global_load_dwordx4 v[114:117], v[8:9], off offset:2048
	global_load_dwordx4 v[118:121], v[10:11], off offset:2048
	v_mov_b32_e32 v8, 0x2a000
	v_mad_u32_u24 v40, v16, s4, v8
	v_mov_b32_e32 v10, 0x31000
	v_lshlrev_b32_e32 v8, 1, v40
	v_mov_b32_e32 v9, v113
	v_mad_u32_u24 v42, v16, s4, v10
	v_lshl_add_u64 v[8:9], v[0:1], 0, v[8:9]
	v_lshlrev_b32_e32 v10, 1, v42
	v_mov_b32_e32 v11, v113
	v_lshl_add_u64 v[0:1], v[0:1], 0, v[10:11]
	global_load_dwordx4 v[122:125], v[8:9], off offset:2048
	global_load_dwordx4 v[126:129], v[0:1], off offset:2048
	global_load_dwordx4 v[146:149], v213, s[38:39]
	s_add_u32 s38, s38, 0xe000
	s_addc_u32 s39, s39, 0
	global_load_dwordx4 v[150:153], v213, s[38:39]
	s_add_u32 s38, s38, 0xe000
	s_addc_u32 s39, s39, 0
	global_load_dwordx4 v[154:157], v213, s[38:39]
	s_add_u32 s38, s38, 0xe000
	s_addc_u32 s39, s39, 0
	global_load_dwordx4 v[158:161], v213, s[38:39]
	v_lshrrev_b32_e32 v14, 2, v12
	v_lshl_add_u64 v[0:1], s[0:1], 0, v[2:3]
	v_lshlrev_b32_e32 v199, 2, v13
	v_lshlrev_b32_e32 v17, 3, v12
	v_lshl_add_u64 v[168:169], v[0:1], 0, v[4:5]
	v_and_or_b32 v2, v14, 3, v199
	v_lshlrev_b32_e32 v3, 1, v12
	v_lshl_add_u64 v[184:185], v[0:1], 0, v[6:7]
	v_and_or_b32 v0, s22, 32, v252
	v_mul_u32_u24_e32 v2, 0x90, v2
	v_and_b32_e32 v35, 32, v3
	v_and_b32_e32 v3, 24, v17
	s_add_i32 s0, s6, s7
	v_or_b32_e32 v0, 0x200, v0
	v_lshlrev_b32_e32 v32, 3, v13
	v_add_u32_e32 v33, v15, v6
	v_add3_u32 v37, v15, v2, v3
	v_mul_u32_u24_e32 v39, 0x90, v16
	s_add_i32 s11, s0, 0xfffffe00
	v_sub_u32_e32 v0, v0, v199
	s_lshl_b32 s0, s29, 6
	v_mov_b32_e32 v251, 0
	v_mov_b32_e32 v248, v224
	v_and_b32_e32 v232, 63, v12
	v_ashrrev_i32_e32 v163, 31, v162
	s_waitcnt lgkmcnt(0)
	v_mov_b32_e32 v167, v166
	v_mov_b32_e32 v170, v166
	v_mov_b32_e32 v171, v166
	v_mov_b32_e32 v172, v166
	v_mov_b32_e32 v173, v166
	v_mov_b32_e32 v174, v166
	v_mov_b32_e32 v175, v166
	v_mov_b32_e32 v176, v166
	v_mov_b32_e32 v177, v166
	v_mov_b32_e32 v178, v166
	v_mov_b32_e32 v179, v166
	v_mov_b32_e32 v180, v166
	v_mov_b32_e32 v181, v166
	v_mov_b32_e32 v182, v166
	v_mov_b32_e32 v183, v166
	v_lshl_add_u64 v[186:187], v[168:169], 0, v[112:113]
	s_add_i32 s28, s29, -1
	v_subrev_u32_e32 v247, s0, v0
	v_mov_b32_e32 v16, v113
	v_mov_b32_e32 v17, v113
	v_mov_b32_e32 v18, v113
	v_mov_b32_e32 v19, v113
	v_mov_b32_e32 v20, v113
	v_mov_b32_e32 v21, v113
	v_mov_b32_e32 v22, v113
	v_mov_b32_e32 v23, v113
	v_mov_b32_e32 v24, v113
	v_mov_b32_e32 v25, v113
	v_mov_b32_e32 v26, v113
	v_mov_b32_e32 v27, v113
	v_mov_b32_e32 v28, v113
	v_mov_b32_e32 v29, v113
	v_mov_b32_e32 v30, v113
	v_mov_b32_e32 v31, v113
	v_mov_b32_e32 v0, v113
	v_mov_b32_e32 v1, v113
	v_mov_b32_e32 v2, v113
	v_mov_b32_e32 v3, v113
	v_mov_b32_e32 v4, v113
	v_mov_b32_e32 v6, v113
	v_mov_b32_e32 v8, v113
	v_mov_b32_e32 v9, v113
	v_mov_b32_e32 v10, v113
	v_mov_b32_e32 v12, v113
	v_mov_b32_e32 v13, v113
	v_mov_b32_e32 v14, v113
	v_mov_b32_e32 v15, v113
	v_mov_b32_e32 v233, 0xf149f2ca
	v_add_u32_e32 v245, v33, v39
	v_lshlrev_b32_e32 v188, 1, v34
	v_lshlrev_b32_e32 v190, 1, v36
	v_lshlrev_b32_e32 v192, 1, v38
	v_lshlrev_b32_e32 v194, 1, v40
	v_lshlrev_b32_e32 v196, 1, v42
	v_lshlrev_b32_e32 v112, 1, v32
	v_add_u32_e32 v250, v37, v35
	s_waitcnt vmcnt(12)
	ds_write_b128 v214, v[80:83]
	ds_write_b128 v214, v[84:87] offset:1152
	ds_write_b128 v214, v[88:91] offset:2304
	ds_write_b128 v214, v[92:95] offset:3456
	s_waitcnt lgkmcnt(0)
	ds_read_b128 v[80:83], v215
	ds_read_b128 v[84:87], v215 offset:32
	ds_read_b128 v[88:91], v215 offset:64
	ds_read_b128 v[92:95], v215 offset:96
	s_waitcnt lgkmcnt(0)
	v_mfma_f32_32x32x16_bf16 v[48:63], v[80:83], v[64:67], 0
	v_mfma_f32_32x32x16_bf16 v[48:63], v[84:87], v[68:71], v[48:63]
	v_mfma_f32_32x32x16_bf16 v[48:63], v[88:91], v[72:75], v[48:63]
	v_mfma_f32_32x32x16_bf16 v[48:63], v[92:95], v[76:79], v[48:63]
.LBB0_264:
	s_waitcnt lgkmcnt(0)
	s_cmp_lg_u32 s28, 7
	s_cselect_b64 s[4:5], -1, 0
	s_cmp_eq_u32 s28, 7
	s_waitcnt vmcnt(4)
	ds_write_b128 v245, v[96:99]
	ds_write_b128 v245, v[100:103] offset:1152
	ds_write_b128 v245, v[104:107] offset:2304
	ds_write_b128 v245, v[108:111] offset:3456
	ds_write_b128 v245, v[114:117] offset:4608
	ds_write_b128 v245, v[118:121] offset:5760
	ds_write_b128 v245, v[122:125] offset:6912
	ds_write_b128 v245, v[126:129] offset:8064
	s_cbranch_scc1 .LBB0_266
	s_add_i32 s0, s11, 64
	v_mad_i64_i32 v[32:33], s[0:1], s0, v238, v[184:185]
	v_mov_b32_e32 v189, v113
	v_lshl_add_u64 v[34:35], v[32:33], 0, v[188:189]
	v_add_co_u32_e32 v36, vcc, 0xe000, v34
	v_mov_b32_e32 v191, v113
	s_nop 0
	v_addc_co_u32_e32 v37, vcc, 0, v35, vcc
	global_load_dwordx4 v[96:99], v[34:35], off offset:2048
	global_load_dwordx4 v[100:103], v[36:37], off offset:2048
	v_add_co_u32_e32 v36, vcc, 0x1c000, v34
	v_mov_b32_e32 v193, v113
	s_nop 0
	v_addc_co_u32_e32 v37, vcc, 0, v35, vcc
	v_add_co_u32_e32 v34, vcc, 0x2a000, v34
	v_mov_b32_e32 v195, v113
	s_nop 0
	v_addc_co_u32_e32 v35, vcc, 0, v35, vcc
	global_load_dwordx4 v[104:107], v[36:37], off offset:2048
	global_load_dwordx4 v[108:111], v[34:35], off offset:2048
	v_lshl_add_u64 v[34:35], v[32:33], 0, v[190:191]
	v_lshl_add_u64 v[36:37], v[32:33], 0, v[192:193]
	global_load_dwordx4 v[114:117], v[34:35], off offset:2048
	global_load_dwordx4 v[118:121], v[36:37], off offset:2048
	v_lshl_add_u64 v[34:35], v[32:33], 0, v[194:195]
	v_mov_b32_e32 v197, v113
	v_lshl_add_u64 v[32:33], v[32:33], 0, v[196:197]
	global_load_dwordx4 v[122:125], v[34:35], off offset:2048
	global_load_dwordx4 v[126:129], v[32:33], off offset:2048
.LBB0_266:
	s_waitcnt lgkmcnt(0)
	ds_read_b64_tr_b16 v[142:143], v250
	ds_read_b64_tr_b16 v[144:145], v250 offset:1152
	ds_read_b64_tr_b16 v[132:133], v250 offset:1216
	ds_read_b64_tr_b16 v[130:131], v250 offset:64
	ds_read_b64_tr_b16 v[138:139], v250 offset:2304
	ds_read_b64_tr_b16 v[140:141], v250 offset:3456
	ds_read_b64_tr_b16 v[136:137], v250 offset:3520
	ds_read_b64_tr_b16 v[134:135], v250 offset:2368
	s_add_i32 s28, s28, 1
	s_cmp_lt_u32 s28, 4
	s_cselect_b64 s[6:7], -1, 0
	s_andn2_b64 vcc, exec, s[4:5]
	s_cbranch_vccnz .Latt_A3_last
	s_waitcnt vmcnt(8)
	ds_write_b128 v214, v[146:149]
	ds_write_b128 v214, v[150:153] offset:1152
	ds_write_b128 v214, v[154:157] offset:2304
	ds_write_b128 v214, v[158:161] offset:3456
	s_add_i32 s38, s11, 64
	s_mul_i32 s38, s38, 0x1c00
	s_add_i32 s38, s38, 0x6000000
	s_add_u32 s38, s2, s38
	s_addc_u32 s39, s3, 0
	global_load_dwordx4 v[146:149], v213, s[38:39]
	s_add_u32 s38, s38, 0xe000
	s_addc_u32 s39, s39, 0
	global_load_dwordx4 v[150:153], v213, s[38:39]
	s_add_u32 s38, s38, 0xe000
	s_addc_u32 s39, s39, 0
	global_load_dwordx4 v[154:157], v213, s[38:39]
	s_add_u32 s38, s38, 0xe000
	s_addc_u32 s39, s39, 0
	global_load_dwordx4 v[158:161], v213, s[38:39]

.LBB0_278:
	ds_read_b128 v[80:83], v215
	ds_read_b128 v[84:87], v215 offset:32
	ds_read_b128 v[88:91], v215 offset:64
	ds_read_b128 v[92:95], v215 offset:96
	v_max_f32_e32 v186, v33, v33
	v_max_f32_e32 v168, v32, v32
	v_max_f32_e32 v186, v168, v186
	v_max3_f32 v186, v186, v34, v35
	v_max3_f32 v186, v186, v36, v37
	v_max3_f32 v186, v186, v38, v39
	v_max3_f32 v186, v186, v40, v41
	v_max3_f32 v186, v186, v42, v43
	v_max3_f32 v186, v186, v44, v45
	v_max3_f32 v186, v186, v46, v47
	v_mov_b32_e32 v168, v186
	v_mov_b32_e32 v169, v186
	s_nop 1
	v_permlane32_swap_b32_e32 v168, v169
	v_max3_f32 v233, v191, v168, v169
	v_add_f32_e32 v186, 0x41000000, v191
	v_cmp_gt_f32_e32 vcc, v233, v186
	s_cbranch_vccnz .Latt_updB
	v_mov_b32_e32 v233, v191
	v_mov_b32_e32 v186, 1.0
	s_branch .LBB0_280
.Latt_updB:
	v_sub_f32_e32 v186, v191, v233
	v_exp_f32_e32 v186, v186
	s_nop 0
	v_pk_mul_f32 v[30:31], v[30:31], v[186:187] op_sel_hi:[1,0]
	v_pk_mul_f32 v[28:29], v[28:29], v[186:187] op_sel_hi:[1,0]
	v_pk_mul_f32 v[26:27], v[26:27], v[186:187] op_sel_hi:[1,0]
	v_pk_mul_f32 v[24:25], v[24:25], v[186:187] op_sel_hi:[1,0]
	v_pk_mul_f32 v[22:23], v[22:23], v[186:187] op_sel_hi:[1,0]
	v_pk_mul_f32 v[20:21], v[20:21], v[186:187] op_sel_hi:[1,0]
	v_pk_mul_f32 v[18:19], v[18:19], v[186:187] op_sel_hi:[1,0]
	v_pk_mul_f32 v[16:17], v[16:17], v[186:187] op_sel_hi:[1,0]
	v_pk_mul_f32 v[14:15], v[14:15], v[186:187] op_sel_hi:[1,0]
	v_pk_mul_f32 v[12:13], v[12:13], v[186:187] op_sel_hi:[1,0]
	v_pk_mul_f32 v[10:11], v[10:11], v[186:187] op_sel_hi:[1,0]
	v_pk_mul_f32 v[8:9], v[8:9], v[186:187] op_sel_hi:[1,0]
	v_pk_mul_f32 v[6:7], v[6:7], v[186:187] op_sel_hi:[1,0]
	v_pk_mul_f32 v[4:5], v[4:5], v[186:187] op_sel_hi:[1,0]
	v_pk_mul_f32 v[2:3], v[2:3], v[186:187] op_sel_hi:[1,0]
	v_pk_mul_f32 v[0:1], v[0:1], v[186:187] op_sel_hi:[1,0]
.LBB0_280:
	s_waitcnt lgkmcnt(0)
	v_mfma_f32_32x32x16_bf16 v[48:63], v[80:83], v[64:67], 0
	v_sub_f32_e32 v32, v32, v233
	v_exp_f32_e32 v32, v32
	v_sub_f32_e32 v33, v33, v233
	v_exp_f32_e32 v33, v33
	v_sub_f32_e32 v34, v34, v233
	v_exp_f32_e32 v34, v34
	v_sub_f32_e32 v35, v35, v233
	v_sub_f32_e32 v36, v36, v233
	v_mfma_f32_32x32x16_bf16 v[48:63], v[84:87], v[68:71], v[48:63]
	v_sub_f32_e32 v37, v37, v233
	v_sub_f32_e32 v38, v38, v233
	v_sub_f32_e32 v39, v39, v233
	v_exp_f32_e32 v35, v35
	v_exp_f32_e32 v36, v36
	v_exp_f32_e32 v37, v37
	v_exp_f32_e32 v38, v38
	v_exp_f32_e32 v39, v39
	v_mfma_f32_32x32x16_bf16 v[48:63], v[88:91], v[72:75], v[48:63]
	v_add_f32_e32 v169, 0, v32
	v_add_f32_e32 v169, v33, v169
	v_add_f32_e32 v168, 0, v193
	v_add_f32_e32 v169, v34, v169
	v_add_f32_e32 v168, v195, v168
	v_add_f32_e32 v169, v35, v169
	v_mfma_f32_32x32x16_bf16 v[48:63], v[92:95], v[76:79], v[48:63]
	v_cvt_pk_bf16_f32 v32, v32, v33
	v_cvt_pk_bf16_f32 v33, v34, v35
	v_cvt_pk_bf16_f32 v34, v36, v37
	v_cvt_pk_bf16_f32 v35, v38, v39
	v_add_f32_e32 v168, v197, v168
	v_add_f32_e32 v168, v200, v168
	s_waitcnt lgkmcnt(0)
	v_mfma_f32_32x32x16_bf16 v[16:31], v[142:145], v[32:35], v[16:31]
	v_add_f32_e32 v168, v201, v168
	v_sub_f32_e32 v40, v40, v233
	v_sub_f32_e32 v41, v41, v233
	v_sub_f32_e32 v42, v42, v233
	v_sub_f32_e32 v43, v43, v233
	v_sub_f32_e32 v44, v44, v233
	v_sub_f32_e32 v45, v45, v233
	v_mfma_f32_32x32x16_bf16 v[0:15], v[134:137], v[32:35], v[0:15]
	v_sub_f32_e32 v46, v46, v233
	v_sub_f32_e32 v47, v47, v233
	v_add_f32_e32 v168, v202, v168
	v_add_f32_e32 v169, v36, v169
	v_exp_f32_e32 v40, v40
	v_exp_f32_e32 v41, v41
	v_exp_f32_e32 v42, v42
	v_exp_f32_e32 v43, v43
	v_exp_f32_e32 v44, v44
	v_exp_f32_e32 v45, v45
	v_exp_f32_e32 v46, v46
	v_exp_f32_e32 v47, v47
	v_add_f32_e32 v168, v203, v168
	v_add_f32_e32 v169, v37, v169
	v_add_f32_e32 v168, v204, v168
	v_add_f32_e32 v169, v38, v169
	v_add_f32_e32 v168, v205, v168
	v_add_f32_e32 v169, v39, v169
	v_add_f32_e32 v168, v206, v168
	v_add_f32_e32 v169, v40, v169
	v_cvt_pk_bf16_f32 v36, v40, v41
	v_cvt_pk_bf16_f32 v37, v42, v43
	v_cvt_pk_bf16_f32 v38, v44, v45
	v_cvt_pk_bf16_f32 v39, v46, v47
	v_add_f32_e32 v168, v207, v168
	v_add_f32_e32 v169, v41, v169
	v_mfma_f32_32x32x16_bf16 v[16:31], v[138:141], v[36:39], v[16:31]
	v_add_f32_e32 v168, v208, v168
	v_add_f32_e32 v169, v42, v169
	v_add_f32_e32 v168, v209, v168
	v_add_f32_e32 v169, v43, v169
	v_add_f32_e32 v168, v210, v168
	v_add_f32_e32 v169, v44, v169
	v_add_f32_e32 v168, v211, v168
	v_mfma_f32_32x32x16_bf16 v[0:15], v[130:133], v[36:39], v[0:15]
	v_add_f32_e32 v169, v45, v169
	v_add_f32_e32 v168, v212, v168
	v_add_f32_e32 v169, v46, v169
	v_fmac_f32_e32 v168, v251, v198
	v_add_f32_e32 v251, v47, v169
	s_add_i32 s11, s11, 64
	v_fmac_f32_e32 v251, v168, v186
	v_subrev_u32_e32 v247, 64, v247
	s_cmp_gt_u32 s28, 7
	s_cbranch_scc1 .LBB0_282
	s_branch .LBB0_264
